# attention rows stored write-through; MIX seam leader skips the L2 writeback when the placement verdict holds
# baseline (speedup 1.0000x reference)
; __device__ __forceinline__ unsigned cvt_pk_bf16(float lo, float hi) { unsigned r; asm volatile("v_cvt_pk_bf16_f32 %0, %1, %2" : "=v"(r) : "v"(lo), "v"(hi)); return r; }
; #define LAS __attribute__((address_space(3)))
; __device__ __forceinline__ void fx_add(i64* p, float v) { atomicAdd((unsigned long long*)p, (unsigned long long)(i64)(v * FX)); }
; __device__ __forceinline__ void attn_unit(LAS unsigned char* lds, int b, int h, int blk, const bf16_t* Q, const bf16_t* Kb, const bf16_t* Vt1, const bf16_t* Vt4, const bf16_t* Vt16,
;                                           bf16_t* MIX, i64* ssq_a, int wid, int lane_in) {
;     ...
;     for (int ps = 0; ps < ABLK / 256; ++ps) {
;       const int tid = wid * 64 + lane, tl = ps * 256 + (tid >> 1), half = tid & 1;
;       const float inv = 1.0f / Ml[2 * tl + 1]; const LAS float* orow = Oacc + tl * OP + 32 * half; float part = 0.f;
;       bf16_t* op = MIX + (tb + T0 + tl) * DM + h * 64 + 32 * half;
; #pragma unroll
;       for (int j = 0; j < 4; ++j) { const f32x4 va = *(const LAS f32x4*)(orow + 8 * j) * inv, vb = *(const LAS f32x4*)(orow + 8 * j + 4) * inv;
;           part += (va[0] * va[0] + va[1] * va[1]) + (va[2] * va[2] + va[3] * va[3]) + (vb[0] * vb[0] + vb[1] * vb[1]) + (vb[2] * vb[2] + vb[3] * vb[3]);
;           u32x4 w; w.x = cvt_pk_bf16(va[0], va[1]); w.y = cvt_pk_bf16(va[2], va[3]); w.z = cvt_pk_bf16(vb[0], vb[1]); w.w = cvt_pk_bf16(vb[2], vb[3]); *(u32x4*)(op + 8 * j) = w; }
;       part += __shfl_xor(part, 1);
;       if (half == 0) fx_add(ssq_a + tb + T0 + tl, part);
;     }
.LBB0_1107:
	v_add_u32_e32 v6, s4, v3
	s_add_i32 s4, 0, 0x22000
	v_lshl_add_u32 v0, v6, 3, s4
	ds_read_b32 v0, v0 offset:4
	s_waitcnt lgkmcnt(0)
	v_div_scale_f32 v7, s[4:5], v0, v0, 1.0
	v_rcp_f32_e32 v8, v7
	s_nop 0
	v_fma_f32 v9, -v7, v8, 1.0
	v_fmac_f32_e32 v8, v9, v8
	v_div_scale_f32 v9, vcc, 1.0, v0, 1.0
	v_mul_f32_e32 v10, v9, v8
	v_fma_f32 v11, -v7, v10, v9
	v_fmac_f32_e32 v10, v11, v8
	v_fma_f32 v7, -v7, v10, v9
	v_div_fmas_f32 v7, v7, v8, v10
	v_mad_u64_u32 v[10:11], s[4:5], v6, s59, v[2:3]
	ds_read_b128 v[14:17], v10
	ds_read_b128 v[18:21], v10 offset:16
	v_div_fixup_f32 v0, v7, v0, 1.0
	v_ashrrev_i32_e32 v7, 31, v6
	v_lshl_add_u64 v[8:9], s[42:43], 0, v[6:7]
	s_waitcnt lgkmcnt(1)
	v_pk_mul_f32 v[16:17], v[16:17], v[0:1] op_sel_hi:[1,0]
	v_pk_mul_f32 v[14:15], v[14:15], v[0:1] op_sel_hi:[1,0]
	v_mul_f32_e32 v13, v17, v17
	v_mul_f32_e32 v11, v15, v15
	s_waitcnt lgkmcnt(0)
	v_pk_mul_f32 v[18:19], v[18:19], v[0:1] op_sel_hi:[1,0]
	v_fmac_f32_e32 v11, v14, v14
	v_fmac_f32_e32 v13, v16, v16
	v_lshlrev_b64 v[8:9], 11, v[8:9]
	v_add_f32_e32 v11, v11, v13
	v_mul_f32_e32 v13, v19, v19
	v_lshl_add_u64 v[8:9], v[4:5], 0, v[8:9]
	v_pk_mul_f32 v[20:21], v[20:21], v[0:1] op_sel_hi:[1,0]
	v_fmac_f32_e32 v13, v18, v18
	v_add_f32_e32 v11, v13, v11
	v_mul_f32_e32 v13, v21, v21
	v_cvt_pk_bf16_f32 v14, v14, v15
	v_cvt_pk_bf16_f32 v15, v16, v17
	v_cvt_pk_bf16_f32 v16, v18, v19
	v_cvt_pk_bf16_f32 v17, v20, v21
	global_store_dwordx4 v[8:9], v[14:17], off sc1
	v_fmac_f32_e32 v13, v20, v20
	ds_read_b128 v[14:17], v10 offset:32
	ds_read_b128 v[18:21], v10 offset:48
	v_add_f32_e32 v11, v13, v11
	s_waitcnt lgkmcnt(1)
	v_pk_mul_f32 v[16:17], v[0:1], v[16:17] op_sel_hi:[0,1]
	v_pk_mul_f32 v[14:15], v[0:1], v[14:15] op_sel_hi:[0,1]
	v_mul_f32_e32 v13, v15, v15
	v_mul_f32_e32 v22, v17, v17
	s_waitcnt lgkmcnt(0)
	v_pk_mul_f32 v[18:19], v[0:1], v[18:19] op_sel_hi:[0,1]
	v_fmac_f32_e32 v13, v14, v14
	v_fmac_f32_e32 v22, v16, v16
	v_add_f32_e32 v13, v13, v22
	v_mul_f32_e32 v22, v19, v19
	v_pk_mul_f32 v[20:21], v[0:1], v[20:21] op_sel_hi:[0,1]
	v_fmac_f32_e32 v22, v18, v18
	v_add_f32_e32 v13, v13, v22
	v_mul_f32_e32 v22, v21, v21
	v_cvt_pk_bf16_f32 v14, v14, v15
	v_cvt_pk_bf16_f32 v15, v16, v17
	v_cvt_pk_bf16_f32 v16, v18, v19
	v_cvt_pk_bf16_f32 v17, v20, v21
	global_store_dwordx4 v[8:9], v[14:17], off offset:16 sc1
	v_fmac_f32_e32 v22, v20, v20
	ds_read_b128 v[14:17], v10 offset:64
	ds_read_b128 v[18:21], v10 offset:80
	v_add_f32_e32 v13, v22, v13
	v_add_f32_e32 v11, v11, v13
	s_waitcnt lgkmcnt(1)
	v_pk_mul_f32 v[16:17], v[0:1], v[16:17] op_sel_hi:[0,1]
	v_pk_mul_f32 v[14:15], v[0:1], v[14:15] op_sel_hi:[0,1]
	v_mul_f32_e32 v13, v15, v15
	v_mul_f32_e32 v22, v17, v17
	s_waitcnt lgkmcnt(0)
	v_pk_mul_f32 v[18:19], v[0:1], v[18:19] op_sel_hi:[0,1]
	v_fmac_f32_e32 v13, v14, v14
	v_fmac_f32_e32 v22, v16, v16
	v_add_f32_e32 v13, v13, v22
	v_mul_f32_e32 v22, v19, v19
	v_pk_mul_f32 v[20:21], v[0:1], v[20:21] op_sel_hi:[0,1]
	v_fmac_f32_e32 v22, v18, v18
	v_add_f32_e32 v13, v13, v22
	v_mul_f32_e32 v22, v21, v21
	v_cvt_pk_bf16_f32 v14, v14, v15
	v_cvt_pk_bf16_f32 v15, v16, v17
	v_cvt_pk_bf16_f32 v16, v18, v19
	v_cvt_pk_bf16_f32 v17, v20, v21
	global_store_dwordx4 v[8:9], v[14:17], off offset:32 sc1
	v_fmac_f32_e32 v22, v20, v20
	ds_read_b128 v[14:17], v10 offset:96
	ds_read_b128 v[18:21], v10 offset:112
	v_add_f32_e32 v13, v22, v13
	v_add_f32_e32 v13, v11, v13
	s_waitcnt lgkmcnt(1)
	v_pk_mul_f32 v[10:11], v[0:1], v[16:17] op_sel_hi:[0,1]
	v_pk_mul_f32 v[14:15], v[0:1], v[14:15] op_sel_hi:[0,1]
	s_waitcnt lgkmcnt(0)
	v_pk_mul_f32 v[20:21], v[0:1], v[20:21] op_sel_hi:[0,1]
	v_pk_mul_f32 v[16:17], v[0:1], v[18:19] op_sel_hi:[0,1]
	v_mul_f32_e32 v0, v15, v15
	v_mul_f32_e32 v18, v11, v11
	v_fmac_f32_e32 v0, v14, v14
	v_fmac_f32_e32 v18, v10, v10
	v_add_f32_e32 v0, v0, v18
	v_mul_f32_e32 v18, v17, v17
	v_fmac_f32_e32 v18, v16, v16
	v_add_f32_e32 v0, v0, v18
	v_mul_f32_e32 v18, v21, v21
	v_fmac_f32_e32 v18, v20, v20
	v_add_f32_e32 v0, v18, v0
	v_add_f32_e32 v0, v13, v0
	v_cvt_pk_bf16_f32 v14, v14, v15
	v_cvt_pk_bf16_f32 v15, v10, v11
	v_cvt_pk_bf16_f32 v16, v16, v17
	v_cvt_pk_bf16_f32 v17, v20, v21
	global_store_dwordx4 v[8:9], v[14:17], off offset:48 sc1
	ds_bpermute_b32 v8, v12, v0
	s_and_saveexec_b64 s[50:51], s[46:47]
	s_cbranch_execz .LBB0_1106
	s_waitcnt lgkmcnt(0)
	v_add_f32_e32 v0, v0, v8
	v_mul_f32_e32 v0, 0x4b800000, v0
	v_trunc_f32_e32 v0, v0
	v_mul_f32_e64 v8, |v0|, s87
	v_floor_f32_e32 v8, v8
	v_fma_f32 v9, v8, s63, |v0|
	v_cvt_u32_f32_e32 v9, v9
	v_cvt_u32_f32_e32 v8, v8
	v_ashrrev_i32_e32 v0, 31, v0
	v_lshl_add_u64 v[6:7], v[6:7], 3, s[30:31]
	v_xor_b32_e32 v10, v8, v0
	v_xor_b32_e32 v8, v9, v0
	v_sub_co_u32_e32 v8, vcc, v8, v0
	s_nop 1
	v_subb_co_u32_e32 v9, vcc, v10, v0, vcc
	global_atomic_add_x2 v[6:7], v[8:9], off
	s_branch .LBB0_1106

; __device__ __forceinline__ unsigned xb_add(unsigned* p, unsigned v) { return __hip_atomic_fetch_add(p, v, __ATOMIC_RELAXED, __HIP_MEMORY_SCOPE_AGENT); }
; __device__ __forceinline__ void xcd_barrier(const XcdBarrier& b) {
;     ...
;         const unsigned old = xb_add(&bar[XB_XSUB(b.x)], 1u);
;         const unsigned gen = old / nloc;
;         if (old + 1u == (gen + 1u) * nloc) {
;             __builtin_amdgcn_fence(__ATOMIC_RELEASE, "agent");
;             asm volatile("s_waitcnt vmcnt(0)" ::: "memory");
;             const unsigned og = xb_add(&bar[XB_TOP], 1u);
;             const unsigned tg = og / nx;
.LBB0_1164:
	s_andn2_saveexec_b64 s[4:5], s[30:31]
	s_cbranch_execz .LBB0_1184
	s_mov_b64 s[30:31], exec
	v_mov_b32_e32 v15, 0x23084
	ds_read_b32 v15, v15
	s_waitcnt lgkmcnt(0)
	v_readfirstlane_b32 s6, v15
	s_nop 3
	s_cmp_lg_u32 s6, 0
	s_cbranch_scc1 .Lmix_skip_wb
	buffer_wbl2 sc1
.Lmix_skip_wb:
	s_waitcnt lgkmcnt(0)
	s_waitcnt vmcnt(0)
	v_mbcnt_lo_u32_b32 v0, s30, 0
	v_mbcnt_hi_u32_b32 v0, s31, v0
	v_cmp_eq_u32_e32 vcc, 0, v0
	s_and_saveexec_b64 s[42:43], vcc
	s_cbranch_execz .LBB0_1167
	s_bcnt1_i32_b64 s4, s[30:31]
	v_mov_b32_e32 v3, s4
	v_readlane_b32 s4, v253, 46
	v_readlane_b32 s5, v253, 47
	s_nop 4
	global_atomic_add v3, v1, v3, s[4:5] sc0
